# attention MODE-0 softmax: max tree as plain v_max3 chain (17 instead of 53 VALU)
# speedup vs baseline: 1.1310x; 1.0036x over previous
; DI float xor32(float v) { return __shfl_xor(v, 32); }
; template <int NDT, int MODE, bool ALLON>
; DI void attn_tile(const bf16_t* Kl, int kst, const bf16_t* Vl, const bf16x8 (&q)[4], f32x16 (&O)[NDT], float& m, float& l,
;                   int kbase, int qp, int win, float cbias, const float* tab, bool lane_on) {
;     ...
;     float tmax = fmaxf(s[0][0], s[1][0]);
; #pragma unroll
;     for (int i = 1; i < 16; ++i) tmax = fmaxf(tmax, fmaxf(s[0][i], s[1][i]));
;     tmax = fmaxf(tmax, xor32(tmax)) + cbias;
; DI void task_nsa(const P& p, int layer, int task, bf16_t* sm, int dm) {
;     ...
;     for (; todo; ++itc) {
;       const int j = __ffsll((long long)todo) - 1;
;       todo &= todo - 1ull;
;       bf16_t* Kl = sm + (itc & 1) * 9216; bf16_t* Vl = Kl + 4608;
;       kv_lstore(R, Kl, Vl);
;       if (todo) kv_gload(R, kg, 128, vg, S_, (__ffsll((long long)todo) - 1) * 64);
;       __syncthreads();
;       const bool on = (mymask >> j) & 1ull;
;       if (j * 64 <= qmin + 31 && __ballot(on)) {
;         if (j * 64 + 63 + 128 <= qmin)
;           attn_tile<2, 0, false>(Kl, 72, Vl, q, O, m, l, j * 64, qp, 0, tab[128], tab, on);
.LBB0_720:
	v_ffbl_b32_e32 v1, v1
	v_ffbl_b32_e32 v0, v0
	v_add_u32_e64 v1, v1, 32 clamp
	v_min_u32_e32 v0, v1, v0
	v_lshlrev_b32_e32 v32, 6, v0
	v_cmp_le_i32_e32 vcc, v32, v138
	s_waitcnt lgkmcnt(0)
	s_barrier
	s_and_saveexec_b64 s[8:9], vcc
	s_cbranch_execz .LBB0_797
	v_lshrrev_b64 v[0:1], v0, v[96:97]
	v_and_b32_e32 v0, 1, v0
	v_cmp_eq_u32_e64 s[4:5], 1, v0
	v_cmp_ne_u32_e32 vcc, 0, v0
	s_cbranch_vccz .LBB0_797
	v_cmp_le_i32_e32 vcc, v32, v137
	s_and_saveexec_b64 s[28:29], vcc
	s_xor_b64 s[28:29], exec, s[28:29]
	s_cbranch_execz .LBB0_727
	v_mov_b32_e32 v0, v195
	ds_read_b32 v144, v135 offset:37376
	s_nop 0
	v_and_b32_e32 v1, 31, v0
	v_lshrrev_b32_e32 v0, 2, v0
	v_mul_u32_u24_e32 v1, 0x48, v1
	v_and_b32_e32 v143, 8, v0
	v_lshlrev_b32_e32 v142, 1, v1
	v_lshlrev_b32_e32 v0, 1, v143
	v_add3_u32 v4, s45, v142, v0
	ds_read_b128 v[0:3], v4
	s_waitcnt lgkmcnt(0)
	v_mfma_f32_32x32x16_bf16 v[48:63], v[0:3], v[64:67], 0
	ds_read_b128 v[0:3], v4 offset:4608
	s_waitcnt lgkmcnt(0)
	v_mfma_f32_32x32x16_bf16 v[32:47], v[0:3], v[64:67], 0
	ds_read_b128 v[0:3], v4 offset:32
	s_waitcnt lgkmcnt(0)
	v_mfma_f32_32x32x16_bf16 v[48:63], v[0:3], v[68:71], v[48:63]
	ds_read_b128 v[0:3], v4 offset:4640
	s_waitcnt lgkmcnt(0)
	v_mfma_f32_32x32x16_bf16 v[32:47], v[0:3], v[68:71], v[32:47]
	ds_read_b128 v[0:3], v4 offset:64
	s_waitcnt lgkmcnt(0)
	v_mfma_f32_32x32x16_bf16 v[48:63], v[0:3], v[72:75], v[48:63]
	ds_read_b128 v[0:3], v4 offset:4672
	s_waitcnt lgkmcnt(0)
	v_mfma_f32_32x32x16_bf16 v[32:47], v[0:3], v[72:75], v[32:47]
	ds_read_b128 v[0:3], v4 offset:4704
	s_waitcnt lgkmcnt(0)
	v_mfma_f32_32x32x16_bf16 v[32:47], v[0:3], v[76:79], v[32:47]
	ds_read_b128 v[0:3], v4 offset:96
	s_waitcnt lgkmcnt(0)
	v_mfma_f32_32x32x16_bf16 v[48:63], v[0:3], v[76:79], v[48:63]
	s_nop 8
	v_max3_f32 v0, v32, v33, v34
	v_max3_f32 v0, v0, v35, v36
	v_max3_f32 v0, v0, v37, v38
	v_max3_f32 v0, v0, v39, v40
	v_max3_f32 v0, v0, v41, v42
	v_max3_f32 v0, v0, v43, v44
	v_max3_f32 v0, v0, v45, v46
	v_max_f32_e32 v0, v0, v47
	v_max3_f32 v1, v48, v49, v50
	v_max3_f32 v1, v1, v51, v52
	v_max3_f32 v1, v1, v53, v54
	v_max3_f32 v1, v1, v55, v56
	v_max3_f32 v1, v1, v57, v58
	v_max3_f32 v1, v1, v59, v60
	v_max3_f32 v1, v1, v61, v62
	v_max_f32_e32 v1, v1, v63
	v_max_f32_e32 v0, v0, v1
	ds_bpermute_b32 v1, v91, v0
	s_waitcnt lgkmcnt(0)
	v_max_f32_e32 v1, v1, v1
	v_max_f32_e32 v0, v0, v1
	v_add_f32_e32 v0, v144, v0
	v_cndmask_b32_e64 v0, v232, v0, s[4:5]
	v_max_f32_e32 v1, v88, v88
	v_max_f32_e32 v141, v1, v0
	v_sub_f32_e32 v0, v88, v141
	v_exp_f32_e32 v88, v0
	s_nop 0
	v_cmp_neq_f32_e32 vcc, 1.0, v88
	s_cbranch_vccz .LBB0_799
	v_pk_mul_f32 v[160:161], v[160:161], v[88:89] op_sel_hi:[1,0]
	v_pk_mul_f32 v[162:163], v[162:163], v[88:89] op_sel_hi:[1,0]
	v_pk_mul_f32 v[164:165], v[164:165], v[88:89] op_sel_hi:[1,0]
	v_pk_mul_f32 v[166:167], v[166:167], v[88:89] op_sel_hi:[1,0]
	v_pk_mul_f32 v[168:169], v[168:169], v[88:89] op_sel_hi:[1,0]
	v_pk_mul_f32 v[170:171], v[170:171], v[88:89] op_sel_hi:[1,0]
	v_pk_mul_f32 v[172:173], v[172:173], v[88:89] op_sel_hi:[1,0]
	v_pk_mul_f32 v[174:175], v[174:175], v[88:89] op_sel_hi:[1,0]
	v_pk_mul_f32 v[176:177], v[176:177], v[88:89] op_sel_hi:[1,0]
	v_pk_mul_f32 v[178:179], v[178:179], v[88:89] op_sel_hi:[1,0]
	v_pk_mul_f32 v[180:181], v[180:181], v[88:89] op_sel_hi:[1,0]
	v_pk_mul_f32 v[182:183], v[182:183], v[88:89] op_sel_hi:[1,0]
	v_pk_mul_f32 v[184:185], v[184:185], v[88:89] op_sel_hi:[1,0]
	v_pk_mul_f32 v[186:187], v[186:187], v[88:89] op_sel_hi:[1,0]
	v_pk_mul_f32 v[188:189], v[188:189], v[88:89] op_sel_hi:[1,0]
	v_pk_mul_f32 v[190:191], v[190:191], v[88:89] op_sel_hi:[1,0]
	s_cbranch_execnz .LBB0_726

; DI float xor32(float v) { return __shfl_xor(v, 32); }
; template <int NDT, int MODE, bool ALLON>
; DI void attn_tile(const bf16_t* Kl, int kst, const bf16_t* Vl, const bf16x8 (&q)[4], f32x16 (&O)[NDT], float& m, float& l,
;                   int kbase, int qp, int win, float cbias, const float* tab, bool lane_on) {
;     ...
;     float tmax = fmaxf(s[0][0], s[1][0]);
; #pragma unroll
;     for (int i = 1; i < 16; ++i) tmax = fmaxf(tmax, fmaxf(s[0][i], s[1][i]));
;     tmax = fmaxf(tmax, xor32(tmax)) + cbias;
; DI void task_nsa(const P& p, int layer, int task, bf16_t* sm, int dm) {
;     ...
;       if (kt * 64 <= qmin + 31 && kt * 64 + 63 + 511 >= qmin) {
;         if (kt * 64 + 63 + 128 <= qmin && qmin + 31 - kt * 64 < 512)
;           attn_tile<2, 0, true>(Kl, 72, Vl, q, O, m, l, kt * 64, qp, 0, tab[128], tab, true);
.LBB0_880:
	s_andn2_saveexec_b64 s[0:1], s[0:1]
	s_cbranch_execz .LBB0_806
	v_mov_b32_e32 v0, v195
	ds_read_b32 v134, v135 offset:37376
	s_nop 0
	v_and_b32_e32 v1, 31, v0
	v_lshrrev_b32_e32 v0, 2, v0
	v_mul_u32_u24_e32 v1, 0x48, v1
	v_and_b32_e32 v133, 8, v0
	v_lshlrev_b32_e32 v132, 1, v1
	v_lshlrev_b32_e32 v0, 1, v133
	v_add3_u32 v4, s25, v132, v0
	ds_read_b128 v[0:3], v4
	s_waitcnt lgkmcnt(0)
	v_mfma_f32_32x32x16_bf16 v[48:63], v[0:3], v[64:67], 0
	ds_read_b128 v[0:3], v4 offset:4608
	s_waitcnt lgkmcnt(0)
	v_mfma_f32_32x32x16_bf16 v[32:47], v[0:3], v[64:67], 0
	ds_read_b128 v[0:3], v4 offset:32
	s_waitcnt lgkmcnt(0)
	v_mfma_f32_32x32x16_bf16 v[48:63], v[0:3], v[68:71], v[48:63]
	ds_read_b128 v[0:3], v4 offset:4640
	s_waitcnt lgkmcnt(0)
	v_mfma_f32_32x32x16_bf16 v[32:47], v[0:3], v[68:71], v[32:47]
	ds_read_b128 v[0:3], v4 offset:64
	s_waitcnt lgkmcnt(0)
	v_mfma_f32_32x32x16_bf16 v[48:63], v[0:3], v[72:75], v[48:63]
	ds_read_b128 v[0:3], v4 offset:4672
	s_waitcnt lgkmcnt(0)
	v_mfma_f32_32x32x16_bf16 v[32:47], v[0:3], v[72:75], v[32:47]
	ds_read_b128 v[0:3], v4 offset:4704
	s_waitcnt lgkmcnt(0)
	v_mfma_f32_32x32x16_bf16 v[32:47], v[0:3], v[76:79], v[32:47]
	ds_read_b128 v[0:3], v4 offset:96
	s_waitcnt lgkmcnt(0)
	v_mfma_f32_32x32x16_bf16 v[48:63], v[0:3], v[76:79], v[48:63]
	s_nop 8
	v_max3_f32 v0, v32, v33, v34
	v_max3_f32 v0, v0, v35, v36
	v_max3_f32 v0, v0, v37, v38
	v_max3_f32 v0, v0, v39, v40
	v_max3_f32 v0, v0, v41, v42
	v_max3_f32 v0, v0, v43, v44
	v_max3_f32 v0, v0, v45, v46
	v_max_f32_e32 v0, v0, v47
	v_max3_f32 v1, v48, v49, v50
	v_max3_f32 v1, v1, v51, v52
	v_max3_f32 v1, v1, v53, v54
	v_max3_f32 v1, v1, v55, v56
	v_max3_f32 v1, v1, v57, v58
	v_max3_f32 v1, v1, v59, v60
	v_max3_f32 v1, v1, v61, v62
	v_max_f32_e32 v1, v1, v63
	v_max_f32_e32 v0, v0, v1
	ds_bpermute_b32 v1, v91, v0
	s_waitcnt lgkmcnt(0)
	v_max_f32_e32 v1, v1, v1
	v_max_f32_e32 v0, v0, v1
	v_add_f32_e32 v0, v134, v0
	v_max_f32_e32 v1, v126, v126
	v_max_f32_e32 v130, v1, v0
	v_sub_f32_e32 v0, v126, v130
	v_exp_f32_e32 v126, v0
	s_nop 0
	v_cmp_neq_f32_e32 vcc, 1.0, v126
	s_cbranch_vccz .LBB0_884
	v_pk_mul_f32 v[0:1], v[124:125], v[126:127] op_sel_hi:[1,0]
	v_pk_mul_f32 v[2:3], v[122:123], v[126:127] op_sel_hi:[1,0]
	v_pk_mul_f32 v[4:5], v[120:121], v[126:127] op_sel_hi:[1,0]
	v_pk_mul_f32 v[6:7], v[118:119], v[126:127] op_sel_hi:[1,0]
	v_pk_mul_f32 v[8:9], v[116:117], v[126:127] op_sel_hi:[1,0]
	v_pk_mul_f32 v[10:11], v[114:115], v[126:127] op_sel_hi:[1,0]
	v_pk_mul_f32 v[12:13], v[110:111], v[126:127] op_sel_hi:[1,0]
	v_pk_mul_f32 v[14:15], v[106:107], v[126:127] op_sel_hi:[1,0]
	v_pk_mul_f32 v[16:17], v[112:113], v[126:127] op_sel_hi:[1,0]
	v_pk_mul_f32 v[18:19], v[108:109], v[126:127] op_sel_hi:[1,0]
	v_pk_mul_f32 v[20:21], v[104:105], v[126:127] op_sel_hi:[1,0]
	v_pk_mul_f32 v[22:23], v[102:103], v[126:127] op_sel_hi:[1,0]
	v_pk_mul_f32 v[24:25], v[100:101], v[126:127] op_sel_hi:[1,0]
	v_pk_mul_f32 v[26:27], v[98:99], v[126:127] op_sel_hi:[1,0]
	v_pk_mul_f32 v[28:29], v[88:89], v[126:127] op_sel_hi:[1,0]
	v_pk_mul_f32 v[30:31], v[96:97], v[126:127] op_sel_hi:[1,0]
	s_cbranch_execnz .LBB0_805
	s_branch .LBB0_804

; template <int NDT, int MODE, bool ALLON>
; DI void attn_tile(const bf16_t* Kl, int kst, const bf16_t* Vl, const bf16x8 (&q)[4], f32x16 (&O)[NDT], float& m, float& l,
;                   int kbase, int qp, int win, float cbias, const float* tab, bool lane_on) {
;     ...
;     float tmax = fmaxf(s[0][0], s[1][0]);
; #pragma unroll
;     for (int i = 1; i < 16; ++i) tmax = fmaxf(tmax, fmaxf(s[0][i], s[1][i]));
;     tmax = fmaxf(tmax, xor32(tmax)) + cbias;
;     if (!ALLON) tmax = lane_on ? tmax : -1e30f;
;     const float mn = fmaxf(m, tmax);
;     alpha = ex2(m - mn);
;     m = mn;
;     const float mc = (ALLON || lane_on) ? mn - cbias : 1e30f;
; #pragma unroll
;     for (int st = 0; st < 2; ++st)
; #pragma unroll
;       for (int i = 0; i < 16; ++i) { const float pe = ex2(s[st][i] - mc); psum += pe; s[st][i] = pe; }
;   } else {
;     float tmax = -1e30f;
; #pragma unroll
;     for (int st = 0; st < 2; ++st)
; #pragma unroll
;       for (int i = 0; i < 16; ++i) {
;         const int key = kbase + st * 32 + 8 * (i >> 2) + 4 * lh + (i & 3);
;         float v;
;         if (MODE == 1) {
;           const int dist = qp - key;
;           const bool ok = (ALLON || lane_on) && dist >= 0 && dist < win;
;           const int di = dist < 0 ? 0 : (dist > 128 ? 128 : dist);
;           v = ok ? s[st][i] + tab[di] : -1e30f;
;         } else {
;           v = (16 * key + 31 <= qp) ? s[st][i] : -1e30f;
;         }
;         s[st][i] = v;
;         tmax = fmaxf(tmax, v);
;       }
;     tmax = fmaxf(tmax, xor32(tmax));
;     const float mn = fmaxf(m, tmax);
;     alpha = ex2(m - mn);
;     m = mn;
; #pragma unroll
;     for (int st = 0; st < 2; ++st)
; #pragma unroll
;       for (int i = 0; i < 16; ++i) {
;         const float pe = s[st][i] > -5e29f ? ex2(s[st][i] - mn) : 0.f;
;         psum += pe;
;         s[st][i] = pe;
;       }
;   }
;   l = l * alpha + psum;
;   if (__ballot(alpha != 1.f)) {
; #pragma unroll
; DI void task_attnA(const P& p, int layer, int task, bf16_t* sm, int dm) {
;     ...
;     if (kt * 64 <= qmin + 31) {
;       bf16x8 q[4];
; #pragma unroll
;       for (int ks = 0; ks < 4; ++ks) q[ks] = qlds[ks * 64];
;       if (kt * 64 + 63 + 128 <= qmin)
;         attn_tile<4, 0, true>(Kl + c * 64, 136, Vl, q, O, m, l, kt * 64, qp, 0, tab[128], tab, true);
;       else
;         attn_tile<4, 1, true>(Kl + c * 64, 136, Vl, q, O, m, l, kt * 64, qp, 1 << 30, 0.f, tab, true);
.LBB0_980:
	v_cmp_le_i32_e32 vcc, s66, v148
	s_waitcnt lgkmcnt(0)
	s_barrier
	s_and_saveexec_b64 s[0:1], vcc
	s_cbranch_execz .LBB0_977
	ds_read_b128 v[64:67], v143
	ds_read_b128 v[120:123], v143 offset:1024
	ds_read_b128 v[116:119], v143 offset:2048
	ds_read_b128 v[112:115], v143 offset:3072
	v_cmp_le_i32_e32 vcc, s66, v149
	v_lshl_add_u32 v69, v144, 1, s9
	s_and_saveexec_b64 s[2:3], vcc
	s_xor_b64 s[2:3], exec, s[2:3]
	s_cbranch_execz .LBB0_985
	v_mov_b32_e32 v68, s81
	ds_read_b32 v155, v68
	v_mov_b32_e32 v68, v195
	s_nop 0
	v_and_b32_e32 v153, 31, v68
	v_lshrrev_b32_e32 v68, 2, v68
	v_and_b32_e32 v152, 8, v68
	v_mul_u32_u24_e32 v70, 0x110, v153
	v_lshlrev_b32_e32 v68, 1, v152
	v_add3_u32 v150, v69, v70, v68
	ds_read_b128 v[68:71], v150
	ds_read_b128 v[156:159], v150 offset:32
	s_waitcnt lgkmcnt(1)
	v_mfma_f32_32x32x16_bf16 v[80:95], v[68:71], v[64:67], 0
	ds_read_b128 v[68:71], v150 offset:8704
	s_waitcnt lgkmcnt(1)
	v_mfma_f32_32x32x16_bf16 v[80:95], v[156:159], v[120:123], v[80:95]
	ds_read_b128 v[156:159], v150 offset:8736
	s_waitcnt lgkmcnt(1)
	v_mfma_f32_32x32x16_bf16 v[64:79], v[68:71], v[64:67], 0
	s_waitcnt lgkmcnt(0)
	v_mfma_f32_32x32x16_bf16 v[64:79], v[156:159], v[120:123], v[64:79]
	ds_read_b128 v[120:123], v150 offset:64
	s_waitcnt lgkmcnt(0)
	v_mfma_f32_32x32x16_bf16 v[80:95], v[120:123], v[116:119], v[80:95]
	ds_read_b128 v[120:123], v150 offset:8768
	s_waitcnt lgkmcnt(0)
	v_mfma_f32_32x32x16_bf16 v[64:79], v[120:123], v[116:119], v[64:79]
	ds_read_b128 v[116:119], v150 offset:8800
	s_waitcnt lgkmcnt(0)
	v_mfma_f32_32x32x16_bf16 v[64:79], v[116:119], v[112:115], v[64:79]
	ds_read_b128 v[116:119], v150 offset:96
	s_waitcnt lgkmcnt(0)
	v_mfma_f32_32x32x16_bf16 v[80:95], v[116:119], v[112:115], v[80:95]
	s_nop 8
	v_max3_f32 v112, v64, v65, v66
	v_max3_f32 v112, v112, v67, v68
	v_max3_f32 v112, v112, v69, v70
	v_max3_f32 v112, v112, v71, v72
	v_max3_f32 v112, v112, v73, v74
	v_max3_f32 v112, v112, v75, v76
	v_max3_f32 v112, v112, v77, v78
	v_max_f32_e32 v112, v112, v79
	v_max3_f32 v113, v80, v81, v82
	v_max3_f32 v113, v113, v83, v84
	v_max3_f32 v113, v113, v85, v86
	v_max3_f32 v113, v113, v87, v88
	v_max3_f32 v113, v113, v89, v90
	v_max3_f32 v113, v113, v91, v92
	v_max3_f32 v113, v113, v93, v94
	v_max_f32_e32 v113, v113, v95
	v_max_f32_e32 v112, v112, v113
	v_and_b32_e32 v114, 64, v231
	v_xor_b32_e32 v113, 32, v231
	v_add_u32_e32 v114, 64, v114
	v_cmp_lt_i32_e32 vcc, v113, v114
	s_nop 1
	v_cndmask_b32_e32 v113, v231, v113, vcc
	v_lshlrev_b32_e32 v113, 2, v113
	ds_bpermute_b32 v113, v113, v112
	s_waitcnt lgkmcnt(0)
	v_max_f32_e32 v113, v113, v113
	v_max_f32_e32 v112, v112, v113
	v_add_f32_e32 v112, v155, v112
	v_max_f32_e32 v113, v154, v154
	v_max_f32_e32 v150, v113, v112
	v_sub_f32_e32 v112, v154, v150
	v_exp_f32_e32 v112, v112
	s_nop 0
	v_cmp_neq_f32_e32 vcc, 1.0, v112
	s_cbranch_vccz .LBB0_984
	v_pk_mul_f32 v[62:63], v[62:63], v[112:113] op_sel_hi:[1,0]
	v_pk_mul_f32 v[60:61], v[60:61], v[112:113] op_sel_hi:[1,0]
	v_pk_mul_f32 v[58:59], v[58:59], v[112:113] op_sel_hi:[1,0]
	v_pk_mul_f32 v[56:57], v[56:57], v[112:113] op_sel_hi:[1,0]
	v_pk_mul_f32 v[54:55], v[54:55], v[112:113] op_sel_hi:[1,0]
	v_pk_mul_f32 v[52:53], v[52:53], v[112:113] op_sel_hi:[1,0]
	v_pk_mul_f32 v[50:51], v[50:51], v[112:113] op_sel_hi:[1,0]
	v_pk_mul_f32 v[48:49], v[48:49], v[112:113] op_sel_hi:[1,0]
	v_pk_mul_f32 v[46:47], v[46:47], v[112:113] op_sel_hi:[1,0]
	v_pk_mul_f32 v[44:45], v[44:45], v[112:113] op_sel_hi:[1,0]
	v_pk_mul_f32 v[42:43], v[42:43], v[112:113] op_sel_hi:[1,0]
	v_pk_mul_f32 v[40:41], v[40:41], v[112:113] op_sel_hi:[1,0]
	v_pk_mul_f32 v[38:39], v[38:39], v[112:113] op_sel_hi:[1,0]
	v_pk_mul_f32 v[36:37], v[36:37], v[112:113] op_sel_hi:[1,0]
	v_pk_mul_f32 v[34:35], v[34:35], v[112:113] op_sel_hi:[1,0]
	v_pk_mul_f32 v[32:33], v[32:33], v[112:113] op_sel_hi:[1,0]
	v_pk_mul_f32 v[30:31], v[30:31], v[112:113] op_sel_hi:[1,0]
	v_pk_mul_f32 v[28:29], v[28:29], v[112:113] op_sel_hi:[1,0]
	v_pk_mul_f32 v[26:27], v[26:27], v[112:113] op_sel_hi:[1,0]
	v_pk_mul_f32 v[24:25], v[24:25], v[112:113] op_sel_hi:[1,0]
	v_pk_mul_f32 v[22:23], v[22:23], v[112:113] op_sel_hi:[1,0]
	v_pk_mul_f32 v[20:21], v[20:21], v[112:113] op_sel_hi:[1,0]
	v_pk_mul_f32 v[18:19], v[18:19], v[112:113] op_sel_hi:[1,0]
	v_pk_mul_f32 v[16:17], v[16:17], v[112:113] op_sel_hi:[1,0]
	v_pk_mul_f32 v[14:15], v[14:15], v[112:113] op_sel_hi:[1,0]
	v_pk_mul_f32 v[12:13], v[12:13], v[112:113] op_sel_hi:[1,0]
	v_pk_mul_f32 v[10:11], v[10:11], v[112:113] op_sel_hi:[1,0]
	v_pk_mul_f32 v[8:9], v[8:9], v[112:113] op_sel_hi:[1,0]
	v_pk_mul_f32 v[6:7], v[6:7], v[112:113] op_sel_hi:[1,0]
	v_pk_mul_f32 v[4:5], v[4:5], v[112:113] op_sel_hi:[1,0]
	v_pk_mul_f32 v[2:3], v[2:3], v[112:113] op_sel_hi:[1,0]
	v_pk_mul_f32 v[0:1], v[0:1], v[112:113] op_sel_hi:[1,0]
